# attention loop: one static s_setprio 1 for waves 4-7 (second-dispatched half) before the loop, reset after
# speedup vs baseline: 1.0046x; 1.0046x over previous
; #define LAS __attribute__((address_space(3)))
; #define DMAT(kt, so) do { const unsigned rb_ = (unsigned)ROWBASE(kt); _Pragma("unroll") for (int r = 0; r < 3; ++r) if (wid + 8 * r < 22) \
;         __builtin_amdgcn_global_load_lds((const unsigned*)(dsrc[r] + (size_t)rb_ * dmul[r]), (LAS unsigned*)(lds + (so) + dlds[r]), 16, 0, 0); } while (0)
; __device__ __forceinline__ void attn_unit2(LAS unsigned char* lds, const bf16_t* __restrict__ Q, const bf16_t* __restrict__ KN, const bf16_t* __restrict__ KPE, ...
;     int tid = tid_in; asm volatile("" : "+v"(tid));
;     const int lane = tid & 63, r32 = lane & 31, hi = lane >> 5, wid = __builtin_amdgcn_readfirstlane(tid >> 6);
;     const bf16_t* qp = Q + (size_t)(qrow0 + wid * 64 + r32) * 768 + h * 96 + hi * 8;
;     bf16x8 qa[6], qb[6];
; #pragma unroll
;     for (int ds = 0; ds < 6; ++ds) { qa[ds] = *(const bf16x8*)(qp + ds * 16); qb[ds] = *(const bf16x8*)(qp + (size_t)32 * 768 + ds * 16); }
;     const int pi = (r32 & 0x13) | ((r32 & 4) << 1) | ((r32 & 8) >> 1);
;     const int ka_off = pi * KROW + hi * 16, va_off = KBUF + r32 * VROW + hi * 16;
;     constexpr int SLOT = KBUF + VBUF;
;     const char* dsrc[3]; unsigned dmul[3]; int dlds[3];
; #pragma unroll
;     for (int r = 0; r < 3; ++r) {
;         const int ii = wid + 8 * r;
;         if (ii < 13) {
;             const int p = 64 * ii + lane, row = p / 13, cc = p % 13;
;             if (cc >= 8 && cc < 12) { dsrc[r] = (const char*)(KPE + (size_t)row * 32 + 8 * (cc - 8)); dmul[r] = 64u; }
;             else { dsrc[r] = (const char*)(KN + (size_t)row * 512 + h * 64 + 8 * (cc == 12 ? 0 : cc)); dmul[r] = 1024u; }
;             dlds[r] = 1024 * ii;
;         } else {
;             const int p = 64 * (ii - 13) + lane, d = p / 9, cc = p % 9;
;             dsrc[r] = (const char*)(VT + (size_t)(h * 64 + (d < 64 ? d : 63)) * MT + 8 * (cc == 8 ? 0 : cc)); dmul[r] = 2u;
;             dlds[r] = KBUF + 1024 * (ii - 13);
;         }
;     }
;     ...
;     DMAT(0, 0);
;     DMAT(1, SLOT);
;     __syncthreads();
;     int sc = 0, sn = SLOT, snn = 2 * SLOT;
;     f32x16 oa0 = {}, oa1 = {}, ob0 = {}, ob1 = {};
;     float ma = -1.0e30f, mb = -1.0e30f, la = 0.f, lb = 0.f;
;     for (int t = 0; t < ntiles; ++t) {
;         __builtin_amdgcn_sched_barrier(0);
;         f32x16 sa0 = {}, sa1 = {}, sb0 = {}, sb1 = {};
.LBB0_354:
	v_and_b32_e32 v0, 19, v3
	v_lshlrev_b32_e32 v1, 1, v3
	v_lshrrev_b32_e32 v3, 1, v3
	v_and_b32_e32 v1, 8, v1
	v_and_b32_e32 v3, 4, v3
	v_or3_b32 v0, v0, v1, v3
	v_mov_b32_e32 v16, v129
	v_mov_b32_e32 v17, v129
	v_mov_b32_e32 v30, v129
	v_mov_b32_e32 v31, v129
	v_mul_u32_u24_e32 v183, 0xd0, v0
	v_mul_u32_u24_e32 v187, 0x90, v2
	v_mov_b32_e32 v18, v129
	v_mov_b32_e32 v19, v129
	v_mov_b32_e32 v20, v129
	v_mov_b32_e32 v21, v129
	v_mov_b32_e32 v22, v129
	v_mov_b32_e32 v23, v129
	v_mov_b32_e32 v24, v129
	v_mov_b32_e32 v25, v129
	v_mov_b32_e32 v26, v129
	v_mov_b32_e32 v27, v129
	v_mov_b32_e32 v28, v129
	v_mov_b32_e32 v29, v129
	v_mov_b64_e32 v[62:63], v[30:31]
	v_mov_b64_e32 v[46:47], v[30:31]
	v_mov_b64_e32 v[0:1], v[16:17]
	s_add_i32 s10, s14, 0x4080
	s_add_i32 s11, s24, 0xffffff80
	s_mov_b32 s24, 0
	v_mov_b32_e32 v191, 0
	v_mov_b32_e32 v194, 0xf149f2ca
	s_mov_b32 s25, 0xb000
	s_movk_i32 s26, 0x5800
	s_mov_b32 s14, 0
	v_mov_b64_e32 v[60:61], v[28:29]
	v_mov_b64_e32 v[58:59], v[26:27]
	v_mov_b64_e32 v[56:57], v[24:25]
	v_mov_b64_e32 v[54:55], v[22:23]
	v_mov_b64_e32 v[52:53], v[20:21]
	v_mov_b64_e32 v[50:51], v[18:19]
	v_mov_b64_e32 v[48:49], v[16:17]
	v_mov_b64_e32 v[44:45], v[28:29]
	v_mov_b64_e32 v[42:43], v[26:27]
	v_mov_b64_e32 v[40:41], v[24:25]
	v_mov_b64_e32 v[38:39], v[22:23]
	v_mov_b64_e32 v[36:37], v[20:21]
	v_mov_b64_e32 v[34:35], v[18:19]
	v_mov_b64_e32 v[32:33], v[16:17]
	v_mov_b64_e32 v[2:3], v[18:19]
	v_mov_b64_e32 v[4:5], v[20:21]
	v_mov_b64_e32 v[6:7], v[22:23]
	v_mov_b64_e32 v[8:9], v[24:25]
	v_mov_b64_e32 v[10:11], v[26:27]
	v_mov_b64_e32 v[12:13], v[28:29]
	v_mov_b64_e32 v[14:15], v[30:31]
	v_mov_b32_e32 v195, 0xf149f2ca
	v_mov_b32_e32 v193, 0
	s_mov_b32 s27, 0
	s_waitcnt vmcnt(0) lgkmcnt(0)
	s_barrier
	s_mov_b32 s34, s14
	v_readlane_b32 s15, v255, 15
	s_nop 3
	s_cmp_lt_u32 s15, 4
	s_cbranch_scc1 .Lat_noprio
	s_setprio 1
.Lat_noprio:
	v_mov_b32_e32 v96, 0
	v_mov_b32_e32 v97, 0
	v_mov_b32_e32 v98, 0
	v_mov_b32_e32 v99, 0
	v_mov_b32_e32 v100, 0
	v_mov_b32_e32 v101, 0
	v_mov_b32_e32 v102, 0
	v_mov_b32_e32 v103, 0
	v_mov_b32_e32 v112, 0
	v_mov_b32_e32 v113, 0
	v_mov_b32_e32 v114, 0
	v_mov_b32_e32 v115, 0
	v_mov_b32_e32 v116, 0
	v_mov_b32_e32 v117, 0
	v_mov_b32_e32 v118, 0
	v_mov_b32_e32 v119, 0
	v_sub_u32_e32 v228, 1, v192
	v_mul_u32_u24_e32 v228, 0xffff, v228
	v_and_b32_e32 v240, 0x3f80, v228
	v_mov_b32_e32 v241, 0
	v_mov_b32_e32 v242, 0
	v_mov_b32_e32 v243, 0
	v_and_b32_e32 v244, 0x4480, v228
	v_mov_b32_e32 v245, 0
	v_mov_b32_e32 v246, 0
	v_mov_b32_e32 v247, 0
	v_mov_b32_e32 v194, 0xc4800000
	v_and_b32_e32 v248, 0x4480, v228
	v_mov_b32_e32 v249, 0
	v_mov_b32_e32 v250, 0
	v_mov_b32_e32 v251, 0
	v_mov_b32_e32 v195, 0xc4800000
	v_add3_u32 v224, s34, v183, v128
	ds_read_b128 v[212:215], v224 offset:0
	ds_read_b128 v[216:219], v224 offset:32
	ds_read_b128 v[220:223], v224 offset:64
	v_mfma_f32_32x32x16_bf16 v[64:79], v[240:243], v[244:247], 0
	v_mfma_f32_32x32x16_bf16 v[80:95], v[240:243], v[248:251], 0
	s_waitcnt lgkmcnt(2)
	v_mfma_f32_32x32x16_bf16 v[64:79], v[212:215], v[130:133], v[64:79]
	v_mfma_f32_32x32x16_bf16 v[80:95], v[212:215], v[138:141], v[80:95]
	ds_read_b128 v[212:215], v224 offset:96
	s_waitcnt lgkmcnt(2)
	v_mfma_f32_32x32x16_bf16 v[64:79], v[216:219], v[134:137], v[64:79]
	v_mfma_f32_32x32x16_bf16 v[80:95], v[216:219], v[142:145], v[80:95]
	ds_read_b128 v[216:219], v224 offset:128
	s_waitcnt lgkmcnt(2)
	v_mfma_f32_32x32x16_bf16 v[64:79], v[220:223], v[146:149], v[64:79]
	v_mfma_f32_32x32x16_bf16 v[80:95], v[220:223], v[154:157], v[80:95]
	ds_read_b128 v[220:223], v224 offset:160
	s_waitcnt lgkmcnt(2)
	v_mfma_f32_32x32x16_bf16 v[64:79], v[212:215], v[150:153], v[64:79]
	v_mfma_f32_32x32x16_bf16 v[80:95], v[212:215], v[158:161], v[80:95]
	s_waitcnt lgkmcnt(1)
	v_mfma_f32_32x32x16_bf16 v[64:79], v[216:219], v[162:165], v[64:79]
	v_mfma_f32_32x32x16_bf16 v[80:95], v[216:219], v[170:173], v[80:95]
	s_waitcnt lgkmcnt(0)
	v_mfma_f32_32x32x16_bf16 v[64:79], v[220:223], v[166:169], v[64:79]
	v_mfma_f32_32x32x16_bf16 v[80:95], v[220:223], v[174:177], v[80:95]
	v_add3_u32 v225, s34, v187, v128
	ds_read_b128 v[196:199], v225 offset:13376
	ds_read_b128 v[200:203], v225 offset:17984
	ds_read_b128 v[204:207], v225 offset:13408
	ds_read_b128 v[208:211], v225 offset:18016
	s_nop 7
	s_nop 3

; __device__ __forceinline__ float xhalf_sum(float m) { auto rr = __builtin_amdgcn_permlane32_swap(__float_as_uint(m), __float_as_uint(m), false, false); return __uint_as_float(rr[0]) + __uint_as_float(rr[1]); }
; __device__ __forceinline__ void attn_unit2(LAS unsigned char* lds, const bf16_t* __restrict__ Q, const bf16_t* __restrict__ KN, const bf16_t* __restrict__ KPE, ...
;     ...
;     }
;     ...
;     const float inva = __builtin_amdgcn_rcpf(xhalf_sum(la)), invb = __builtin_amdgcn_rcpf(xhalf_sum(lb));
.Lat_done:
	s_setprio 0
	s_nop 15
